# final RMSNorm writes the output with write-through (sc1) stores: less dirty data left in L2 at kernel end
# speedup vs baseline: 1.0003x; 1.0003x over previous
; #define GAS __attribute__((address_space(1)))
; __device__ __forceinline__ void final_norm_phase(Frame& F, float* out, const bf16* HB, const float* ssq, const float* gf) {
;     ...
;     for (int m0 = 4 * gw; m0 < M; m0 += 4 * NGW) {
;         float sp[4]; v2u hw[4][4];
; #pragma unroll
;         for (int j = 0; j < 4; ++j) { const int m = m0 + j; sp[j] = F.lane < 16 ? pg8::ld_agent(ssq + (size_t)F.lane * M + m) : 0.f;
;             const GAS v2u* hr = (const GAS v2u*)(HB + (size_t)m * D) + F.lane;
; #pragma unroll
;             for (int jj = 0; jj < 4; ++jj) hw[j][jj] = hr[64 * jj]; }
; #pragma unroll
;         for (int j = 0; j < 4; ++j) { const float r = __builtin_amdgcn_rsqf(wave_sum(sp[j]) * (1.0f / 1024.0f) + pg8::RMS_EPS);
;             GAS f32x4* xr = (GAS f32x4*)(out + (size_t)(m0 + j) * D) + F.lane;
;             xr[0]   = (f32x4){bflo(hw[j][0].x), bfhi(hw[j][0].x), bflo(hw[j][0].y), bfhi(hw[j][0].y)} * r * g0;
;             xr[64]  = (f32x4){bflo(hw[j][1].x), bfhi(hw[j][1].x), bflo(hw[j][1].y), bfhi(hw[j][1].y)} * r * g1;
;             xr[128] = (f32x4){bflo(hw[j][2].x), bfhi(hw[j][2].x), bflo(hw[j][2].y), bfhi(hw[j][2].y)} * r * g2;
;             xr[192] = (f32x4){bflo(hw[j][3].x), bfhi(hw[j][3].x), bflo(hw[j][3].y), bfhi(hw[j][3].y)} * r * g3; }
.LBB0_830:
	s_or_b64 exec, exec, s[2:3]
	s_waitcnt vmcnt(0)
	ds_bpermute_b32 v42, v50, v60
	v_lshlrev_b32_e32 v62, 16, v40
	v_and_b32_e32 v63, 0xffff0000, v40
	v_lshlrev_b32_e32 v68, 16, v36
	v_and_b32_e32 v69, 0xffff0000, v36
	s_waitcnt lgkmcnt(0)
	v_add_f32_e32 v42, v60, v42
	ds_bpermute_b32 v43, v51, v42
	v_add_co_u32_e32 v60, vcc, 0x5a01000, v28
	ds_bpermute_b32 v73, v50, v59
	v_lshlrev_b32_e32 v64, 16, v41
	s_waitcnt lgkmcnt(1)
	v_add_f32_e32 v28, v42, v43
	ds_bpermute_b32 v42, v52, v28
	v_and_b32_e32 v65, 0xffff0000, v41
	v_addc_co_u32_e32 v61, vcc, 0, v29, vcc
	v_add_co_u32_e64 v66, s[2:3], s5, v16
	s_waitcnt lgkmcnt(0)
	v_add_f32_e32 v28, v28, v42
	ds_bpermute_b32 v40, v53, v28
	v_lshlrev_b32_e32 v70, 16, v37
	v_and_b32_e32 v71, 0xffff0000, v37
	v_addc_co_u32_e64 v67, s[2:3], -1, v17, s[2:3]
	s_waitcnt lgkmcnt(0)
	v_add_f32_e32 v28, v28, v40
	ds_bpermute_b32 v40, v54, v28
	v_add_f32_e32 v59, v59, v73
	s_add_i32 s4, s4, s6
	v_lshl_add_u64 v[18:19], v[18:19], 0, s[10:11]
	s_cmp_lt_i32 s4, s101
	s_waitcnt lgkmcnt(0)
	v_add_f32_e32 v28, v28, v40
	ds_bpermute_b32 v36, v55, v28
	v_lshl_add_u64 v[20:21], v[20:21], 0, s[12:13]
	s_waitcnt lgkmcnt(0)
	v_add_f32_e32 v28, v28, v36
	v_fmamk_f32 v28, v28, 0x3a800000, v56
	v_rsq_f32_e32 v72, v28
	global_load_dwordx2 v[42:43], v[60:61], off offset:2048
	global_load_dwordx2 v[40:41], v[60:61], off offset:2560
	global_load_dwordx2 v[36:37], v[60:61], off offset:3072
	global_load_dwordx2 v[28:29], v[60:61], off offset:3584
	v_pk_mul_f32 v[60:61], v[72:73], v[62:63] op_sel_hi:[0,1]
	v_pk_mul_f32 v[62:63], v[72:73], v[64:65] op_sel_hi:[0,1]
	v_pk_mul_f32 v[68:69], v[72:73], v[68:69] op_sel_hi:[0,1]
	v_pk_mul_f32 v[64:65], v[72:73], v[70:71] op_sel_hi:[0,1]
	v_pk_mul_f32 v[62:63], v[2:3], v[62:63]
	v_pk_mul_f32 v[60:61], v[0:1], v[60:61]
	v_pk_mul_f32 v[64:65], v[6:7], v[64:65]
	global_store_dwordx4 v[66:67], v[60:63], off offset:-3072 sc1
	s_nop 1
	v_pk_mul_f32 v[62:63], v[4:5], v[68:69]
	global_store_dwordx4 v[66:67], v[62:65], off offset:-2048 sc1
	ds_bpermute_b32 v62, v51, v59
	v_lshlrev_b32_e32 v60, 16, v48
	v_and_b32_e32 v61, 0xffff0000, v48
	v_lshlrev_b32_e32 v48, 16, v49
	v_and_b32_e32 v49, 0xffff0000, v49
	s_waitcnt lgkmcnt(0)
	v_add_f32_e32 v59, v59, v62
	ds_bpermute_b32 v64, v52, v59
	v_pk_mul_f32 v[60:61], v[72:73], v[60:61] op_sel_hi:[0,1]
	v_pk_mul_f32 v[48:49], v[72:73], v[48:49] op_sel_hi:[0,1]
	v_pk_mul_f32 v[62:63], v[10:11], v[48:49]
	v_pk_mul_f32 v[60:61], v[8:9], v[60:61]
	s_waitcnt lgkmcnt(0)
	v_add_f32_e32 v59, v59, v64
	global_store_dwordx4 v[66:67], v[60:63], off offset:-1024 sc1
	ds_bpermute_b32 v60, v53, v59
	v_lshlrev_b32_e32 v48, 16, v44
	v_and_b32_e32 v49, 0xffff0000, v44
	v_lshlrev_b32_e32 v44, 16, v45
	v_and_b32_e32 v45, 0xffff0000, v45
	s_waitcnt lgkmcnt(0)
	v_add_f32_e32 v59, v59, v60
	ds_bpermute_b32 v64, v54, v59
	v_pk_mul_f32 v[44:45], v[72:73], v[44:45] op_sel_hi:[0,1]
	v_pk_mul_f32 v[62:63], v[14:15], v[44:45]
	v_pk_mul_f32 v[48:49], v[72:73], v[48:49] op_sel_hi:[0,1]
	v_pk_mul_f32 v[60:61], v[12:13], v[48:49]
	s_waitcnt lgkmcnt(0)
	v_add_f32_e32 v44, v59, v64
	ds_bpermute_b32 v45, v55, v44
	v_add_co_u32_e32 v48, vcc, s7, v16
	ds_bpermute_b32 v59, v50, v58
	s_nop 0
	v_addc_co_u32_e32 v49, vcc, -1, v17, vcc
	s_waitcnt lgkmcnt(1)
	v_add_f32_e32 v44, v44, v45
	v_fmamk_f32 v44, v44, 0x3a800000, v56
	global_store_dwordx4 v[48:49], v[60:63], off offset:-4096 sc1
	v_and_b32_e32 v45, 0xffff0000, v46
	s_waitcnt lgkmcnt(0)
	v_add_f32_e32 v58, v58, v59
	v_rsq_f32_e32 v60, v44
	v_lshlrev_b32_e32 v44, 16, v46
	v_lshlrev_b32_e32 v46, 16, v47
	v_and_b32_e32 v47, 0xffff0000, v47
	v_pk_mul_f32 v[44:45], v[60:61], v[44:45] op_sel_hi:[0,1]
	v_pk_mul_f32 v[46:47], v[60:61], v[46:47] op_sel_hi:[0,1]
	ds_bpermute_b32 v59, v51, v58
	v_pk_mul_f32 v[46:47], v[2:3], v[46:47]
	v_pk_mul_f32 v[44:45], v[0:1], v[44:45]
	global_store_dwordx4 v[48:49], v[44:47], off offset:-3072 sc1
	s_nop 1
	v_lshlrev_b32_e32 v44, 16, v38
	v_and_b32_e32 v45, 0xffff0000, v38
	v_lshlrev_b32_e32 v38, 16, v39
	v_and_b32_e32 v39, 0xffff0000, v39
	v_pk_mul_f32 v[44:45], v[60:61], v[44:45] op_sel_hi:[0,1]
	v_pk_mul_f32 v[38:39], v[60:61], v[38:39] op_sel_hi:[0,1]
	v_pk_mul_f32 v[46:47], v[6:7], v[38:39]
	v_pk_mul_f32 v[44:45], v[4:5], v[44:45]
	global_store_dwordx4 v[48:49], v[44:47], off offset:-2048 sc1
	v_lshlrev_b32_e32 v38, 16, v34
	v_and_b32_e32 v39, 0xffff0000, v34
	s_waitcnt lgkmcnt(0)
	v_add_f32_e32 v44, v58, v59
	ds_bpermute_b32 v45, v52, v44
	v_pk_mul_f32 v[38:39], v[60:61], v[38:39] op_sel_hi:[0,1]
	v_lshlrev_b32_e32 v34, 16, v35
	v_and_b32_e32 v35, 0xffff0000, v35
	v_pk_mul_f32 v[34:35], v[60:61], v[34:35] op_sel_hi:[0,1]
	s_waitcnt lgkmcnt(0)
	v_add_f32_e32 v58, v44, v45
	ds_bpermute_b32 v59, v53, v58
	v_pk_mul_f32 v[44:45], v[8:9], v[38:39]
	v_pk_mul_f32 v[46:47], v[10:11], v[34:35]
	v_lshlrev_b32_e32 v34, 16, v30
	v_and_b32_e32 v35, 0xffff0000, v30
	s_waitcnt lgkmcnt(0)
; #define GAS __attribute__((address_space(1)))
; __device__ __forceinline__ void final_norm_phase(Frame& F, float* out, const bf16* HB, const float* ssq, const float* gf) {
;     ...
; #pragma unroll
;         for (int j = 0; j < 4; ++j) { const float r = __builtin_amdgcn_rsqf(wave_sum(sp[j]) * (1.0f / 1024.0f) + pg8::RMS_EPS);
;             GAS f32x4* xr = (GAS f32x4*)(out + (size_t)(m0 + j) * D) + F.lane;
;             xr[0]   = (f32x4){bflo(hw[j][0].x), bfhi(hw[j][0].x), bflo(hw[j][0].y), bfhi(hw[j][0].y)} * r * g0;
;             xr[64]  = (f32x4){bflo(hw[j][1].x), bfhi(hw[j][1].x), bflo(hw[j][1].y), bfhi(hw[j][1].y)} * r * g1;
;             xr[128] = (f32x4){bflo(hw[j][2].x), bfhi(hw[j][2].x), bflo(hw[j][2].y), bfhi(hw[j][2].y)} * r * g2;
;             xr[192] = (f32x4){bflo(hw[j][3].x), bfhi(hw[j][3].x), bflo(hw[j][3].y), bfhi(hw[j][3].y)} * r * g3; }
	v_add_f32_e32 v38, v58, v59
	ds_bpermute_b32 v39, v54, v38
	v_lshlrev_b32_e32 v30, 16, v31
	v_and_b32_e32 v31, 0xffff0000, v31
	v_pk_mul_f32 v[30:31], v[60:61], v[30:31] op_sel_hi:[0,1]
	global_store_dwordx4 v[48:49], v[44:47], off offset:-1024 sc1
	s_waitcnt lgkmcnt(0)
	v_add_f32_e32 v38, v38, v39
	ds_bpermute_b32 v39, v55, v38
	v_pk_mul_f32 v[46:47], v[14:15], v[30:31]
	v_pk_mul_f32 v[34:35], v[60:61], v[34:35] op_sel_hi:[0,1]
	v_pk_mul_f32 v[44:45], v[12:13], v[34:35]
	v_and_b32_e32 v31, 0xffff0000, v32
	s_waitcnt lgkmcnt(0)
	v_add_f32_e32 v30, v38, v39
	v_fmamk_f32 v30, v30, 0x3a800000, v56
	v_rsq_f32_e32 v34, v30
	v_lshlrev_b32_e32 v30, 16, v32
	v_lshlrev_b32_e32 v32, 16, v33
	v_and_b32_e32 v33, 0xffff0000, v33
	v_pk_mul_f32 v[30:31], v[34:35], v[30:31] op_sel_hi:[0,1]
	v_pk_mul_f32 v[32:33], v[34:35], v[32:33] op_sel_hi:[0,1]
	ds_bpermute_b32 v35, v50, v57
	v_add_co_u32_e32 v38, vcc, s14, v16
	v_pk_mul_f32 v[32:33], v[2:3], v[32:33]
	v_pk_mul_f32 v[30:31], v[0:1], v[30:31]
	v_addc_co_u32_e32 v39, vcc, -1, v17, vcc
	global_store_dwordx4 v[38:39], v[30:33], off offset:-3072 sc1
	global_store_dwordx4 v[48:49], v[44:47], off sc1
	s_nop 0
	v_lshlrev_b32_e32 v30, 16, v26
	v_and_b32_e32 v31, 0xffff0000, v26
	v_lshlrev_b32_e32 v26, 16, v27
	v_and_b32_e32 v27, 0xffff0000, v27
	s_waitcnt lgkmcnt(0)
	v_pk_mul_f32 v[30:31], v[34:35], v[30:31] op_sel_hi:[0,1]
	v_pk_mul_f32 v[26:27], v[34:35], v[26:27] op_sel_hi:[0,1]
	v_add_f32_e32 v35, v57, v35
	ds_bpermute_b32 v44, v51, v35
	v_pk_mul_f32 v[32:33], v[6:7], v[26:27]
	v_pk_mul_f32 v[30:31], v[4:5], v[30:31]
	global_store_dwordx4 v[38:39], v[30:33], off offset:-2048 sc1
	v_lshlrev_b32_e32 v26, 16, v24
	v_and_b32_e32 v27, 0xffff0000, v24
	s_waitcnt lgkmcnt(0)
	v_add_f32_e32 v32, v35, v44
	ds_bpermute_b32 v33, v52, v32
	v_lshlrev_b32_e32 v24, 16, v25
	v_and_b32_e32 v25, 0xffff0000, v25
	v_pk_mul_f32 v[30:31], v[34:35], v[26:27] op_sel_hi:[0,1]
	v_pk_mul_f32 v[24:25], v[34:35], v[24:25] op_sel_hi:[0,1]
	s_waitcnt lgkmcnt(0)
	v_add_f32_e32 v32, v32, v33
	ds_bpermute_b32 v33, v53, v32
	v_pk_mul_f32 v[26:27], v[10:11], v[24:25]
	v_pk_mul_f32 v[24:25], v[8:9], v[30:31]
	global_store_dwordx4 v[38:39], v[24:27], off offset:-1024 sc1
	s_waitcnt lgkmcnt(0)
	v_add_f32_e32 v30, v32, v33
	ds_bpermute_b32 v31, v54, v30
	v_lshlrev_b32_e32 v24, 16, v22
	v_and_b32_e32 v25, 0xffff0000, v22
	v_lshlrev_b32_e32 v22, 16, v23
	v_and_b32_e32 v23, 0xffff0000, v23
	s_waitcnt lgkmcnt(0)
	v_add_f32_e32 v30, v30, v31
	ds_bpermute_b32 v31, v55, v30
	v_pk_mul_f32 v[26:27], v[34:35], v[24:25] op_sel_hi:[0,1]
	v_pk_mul_f32 v[22:23], v[34:35], v[22:23] op_sel_hi:[0,1]
	v_pk_mul_f32 v[24:25], v[14:15], v[22:23]
	v_pk_mul_f32 v[22:23], v[12:13], v[26:27]
	global_store_dwordx4 v[16:17], v[22:25], off offset:-4096 sc1
	s_waitcnt lgkmcnt(0)
	s_nop 0
	v_add_f32_e32 v22, v30, v31
	v_fmamk_f32 v22, v22, 0x3a800000, v56
	v_rsq_f32_e32 v26, v22
	s_waitcnt vmcnt(15)
	v_lshlrev_b32_e32 v22, 16, v42
	v_and_b32_e32 v23, 0xffff0000, v42
	v_lshlrev_b32_e32 v24, 16, v43
	v_and_b32_e32 v25, 0xffff0000, v43
	v_pk_mul_f32 v[22:23], v[26:27], v[22:23] op_sel_hi:[0,1]
	v_pk_mul_f32 v[24:25], v[26:27], v[24:25] op_sel_hi:[0,1]
	v_pk_mul_f32 v[24:25], v[2:3], v[24:25]
	v_pk_mul_f32 v[22:23], v[0:1], v[22:23]
	global_store_dwordx4 v[16:17], v[22:25], off offset:-3072 sc1
	s_waitcnt vmcnt(15)
	s_nop 0
	v_lshlrev_b32_e32 v22, 16, v40
	v_and_b32_e32 v23, 0xffff0000, v40
	v_lshlrev_b32_e32 v24, 16, v41
	v_and_b32_e32 v25, 0xffff0000, v41
	v_pk_mul_f32 v[22:23], v[26:27], v[22:23] op_sel_hi:[0,1]
	v_pk_mul_f32 v[24:25], v[26:27], v[24:25] op_sel_hi:[0,1]
	v_pk_mul_f32 v[24:25], v[6:7], v[24:25]
	v_pk_mul_f32 v[22:23], v[4:5], v[22:23]
	global_store_dwordx4 v[16:17], v[22:25], off offset:-2048 sc1
	s_waitcnt vmcnt(15)
	s_nop 0
	v_lshlrev_b32_e32 v22, 16, v36
	v_and_b32_e32 v23, 0xffff0000, v36
	v_lshlrev_b32_e32 v24, 16, v37
	v_and_b32_e32 v25, 0xffff0000, v37
	v_pk_mul_f32 v[22:23], v[26:27], v[22:23] op_sel_hi:[0,1]
	v_pk_mul_f32 v[24:25], v[26:27], v[24:25] op_sel_hi:[0,1]
	v_pk_mul_f32 v[24:25], v[10:11], v[24:25]
	v_pk_mul_f32 v[22:23], v[8:9], v[22:23]
	global_store_dwordx4 v[16:17], v[22:25], off offset:-1024 sc1
	s_waitcnt vmcnt(15)
	s_nop 0
	v_lshlrev_b32_e32 v22, 16, v28
	v_and_b32_e32 v23, 0xffff0000, v28
	v_lshlrev_b32_e32 v24, 16, v29
	v_and_b32_e32 v25, 0xffff0000, v29
	v_pk_mul_f32 v[22:23], v[26:27], v[22:23] op_sel_hi:[0,1]
	v_pk_mul_f32 v[24:25], v[26:27], v[24:25] op_sel_hi:[0,1]
	v_pk_mul_f32 v[24:25], v[14:15], v[24:25]
	v_pk_mul_f32 v[22:23], v[12:13], v[22:23]
	global_store_dwordx4 v[16:17], v[22:25], off sc1
	v_lshl_add_u64 v[16:17], v[16:17], 0, s[8:9]
	s_cbranch_scc0 .LBB0_839
